# merged GEMM gate epilogue: gate-ratio packed multiplies write the accumulators in place, 8 copy v_mov per group removed (128 per unit epilogue)
# speedup vs baseline: 1.0007x; 1.0007x over previous
; __device__ __forceinline__ u32x4 pack8(const f32x4 a, const f32x4 b) { u32x4 w; w.x = cvt_pk_bf16(a[0], a[1]); w.y = cvt_pk_bf16(a[2], a[3]); w.z = cvt_pk_bf16(b[0], b[1]); w.w = cvt_pk_bf16(b[2], b[3]); return w; }
; __device__ __forceinline__ float clampg(unsigned bits) { return __uint_as_float(bits > 0x0da24260u ? bits : 0x0da24260u); }
;     __device__ __forceinline__ void operator()(acc_t& acc, const Unit& u, int wr, int wc, int fr, int fq) const {
;     ...
;             for (int m = 0; m < 4; ++m)
; #pragma unroll
;                 for (int bj = 0; bj < 2; ++bj) {
;                     const u32x4 a = ga[m][bj]; float f[8] = {clampg(a.x << 16), clampg(a.x & 0xffff0000u), clampg(a.y << 16), clampg(a.y & 0xffff0000u), clampg(a.z << 16), clampg(a.z & 0xffff0000u), clampg(a.w << 16), clampg(a.w & 0xffff0000u)};
;                     if (br < 2) { const u32x4 b = gb[m][bj]; const float d[8] = {clampg(b.x << 16), clampg(b.x & 0xffff0000u), clampg(b.y << 16), clampg(b.y & 0xffff0000u), clampg(b.z << 16), clampg(b.z & 0xffff0000u), clampg(b.w << 16), clampg(b.w & 0xffff0000u)};
; #pragma unroll
;                         for (int e = 0; e < 8; ++e) f[e] *= __builtin_amdgcn_rcpf(d[e]); }
;                     f32x4 x0 = acc[ai][bj][m][0], x1 = acc[ai][bj][m][1];
;                     x0[0] *= f[0]; x0[1] *= f[1]; x0[2] *= f[2]; x0[3] *= f[3]; x1[0] *= f[4]; x1[1] *= f[5]; x1[2] *= f[6]; x1[3] *= f[7];
;                     if (br < 2) { acc[ai][bj][m][0] = x0; acc[ai][bj][m][1] = x1; }
;                     else *(u32x4*)(O + (size_t)(ai * HALF + m * 16) * D + HALF * bj) = pack8(x0, x1);
.LBB0_601:
	v_readlane_b32 s2, v247, 53
	v_readlane_b32 s3, v247, 54
	v_pk_mul_f32 v[126:127], v[126:127], v[204:205]
	v_pk_mul_f32 v[128:129], v[128:129], v[202:203]
	v_lshl_add_u64 v[196:197], v[196:197], 1, s[2:3]
	v_pk_mul_f32 v[122:123], v[122:123], v[206:207]
	s_and_b64 vcc, exec, s[6:7]
	v_pk_mul_f32 v[124:125], v[124:125], v[190:191]
	s_cbranch_vccnz .LBB0_603
	v_cvt_pk_bf16_f32 v214, v126, v127
	v_cvt_pk_bf16_f32 v215, v128, v129
	v_cvt_pk_bf16_f32 v216, v122, v123
	v_cvt_pk_bf16_f32 v217, v124, v125
	global_store_dwordx4 v[196:197], v[214:217], off
	s_branch .LBB0_604
.LBB0_603:
.LBB0_604:
	s_and_b64 vcc, exec, s[4:5]
	s_cbranch_vccnz .Lp3g_0
	v_add_co_u32_e32 v244, vcc, 0x40000, v198
	s_nop 1
	v_addc_co_u32_e32 v245, vcc, 0, v199, vcc
	global_load_dwordx4 v[158:161], v[244:245], off

; __device__ __forceinline__ u32x4 pack8(const f32x4 a, const f32x4 b) { u32x4 w; w.x = cvt_pk_bf16(a[0], a[1]); w.y = cvt_pk_bf16(a[2], a[3]); w.z = cvt_pk_bf16(b[0], b[1]); w.w = cvt_pk_bf16(b[2], b[3]); return w; }
; __device__ __forceinline__ float clampg(unsigned bits) { return __uint_as_float(bits > 0x0da24260u ? bits : 0x0da24260u); }
;     __device__ __forceinline__ void operator()(acc_t& acc, const Unit& u, int wr, int wc, int fr, int fq) const {
;     ...
;             for (int m = 0; m < 4; ++m)
; #pragma unroll
;                 for (int bj = 0; bj < 2; ++bj) {
;                     const u32x4 a = ga[m][bj]; float f[8] = {clampg(a.x << 16), clampg(a.x & 0xffff0000u), clampg(a.y << 16), clampg(a.y & 0xffff0000u), clampg(a.z << 16), clampg(a.z & 0xffff0000u), clampg(a.w << 16), clampg(a.w & 0xffff0000u)};
;                     if (br < 2) { const u32x4 b = gb[m][bj]; const float d[8] = {clampg(b.x << 16), clampg(b.x & 0xffff0000u), clampg(b.y << 16), clampg(b.y & 0xffff0000u), clampg(b.z << 16), clampg(b.z & 0xffff0000u), clampg(b.w << 16), clampg(b.w & 0xffff0000u)};
; #pragma unroll
;                         for (int e = 0; e < 8; ++e) f[e] *= __builtin_amdgcn_rcpf(d[e]); }
;                     f32x4 x0 = acc[ai][bj][m][0], x1 = acc[ai][bj][m][1];
;                     x0[0] *= f[0]; x0[1] *= f[1]; x0[2] *= f[2]; x0[3] *= f[3]; x1[0] *= f[4]; x1[1] *= f[5]; x1[2] *= f[6]; x1[3] *= f[7];
;                     if (br < 2) { acc[ai][bj][m][0] = x0; acc[ai][bj][m][1] = x1; }
;                     else *(u32x4*)(O + (size_t)(ai * HALF + m * 16) * D + HALF * bj) = pack8(x0, x1);
.LBB0_608:
	v_pk_mul_f32 v[94:95], v[94:95], v[192:193]
	v_pk_mul_f32 v[96:97], v[96:97], v[190:191]
	v_pk_mul_f32 v[90:91], v[90:91], v[202:203]
	s_and_b64 vcc, exec, s[6:7]
	v_pk_mul_f32 v[92:93], v[92:93], v[186:187]
	s_cbranch_vccnz .LBB0_610
	v_cvt_pk_bf16_f32 v188, v94, v95
	v_cvt_pk_bf16_f32 v189, v96, v97
	v_cvt_pk_bf16_f32 v190, v90, v91
	v_cvt_pk_bf16_f32 v191, v92, v93
	global_store_dwordx4 v[196:197], v[188:191], off offset:256
	s_branch .LBB0_611
.LBB0_610:
.LBB0_611:
	s_and_b64 vcc, exec, s[4:5]
	s_cbranch_vccnz .Lp3g_1
	v_add_co_u32_e32 v244, vcc, 0x40000, v198
	s_nop 1
	v_addc_co_u32_e32 v245, vcc, 0, v199, vcc
	global_load_dwordx4 v[154:157], v[244:245], off offset:256

; __device__ __forceinline__ u32x4 pack8(const f32x4 a, const f32x4 b) { u32x4 w; w.x = cvt_pk_bf16(a[0], a[1]); w.y = cvt_pk_bf16(a[2], a[3]); w.z = cvt_pk_bf16(b[0], b[1]); w.w = cvt_pk_bf16(b[2], b[3]); return w; }
; __device__ __forceinline__ float clampg(unsigned bits) { return __uint_as_float(bits > 0x0da24260u ? bits : 0x0da24260u); }
;     __device__ __forceinline__ void operator()(acc_t& acc, const Unit& u, int wr, int wc, int fr, int fq) const {
;     ...
;             for (int m = 0; m < 4; ++m)
; #pragma unroll
;                 for (int bj = 0; bj < 2; ++bj) {
;                     const u32x4 a = ga[m][bj]; float f[8] = {clampg(a.x << 16), clampg(a.x & 0xffff0000u), clampg(a.y << 16), clampg(a.y & 0xffff0000u), clampg(a.z << 16), clampg(a.z & 0xffff0000u), clampg(a.w << 16), clampg(a.w & 0xffff0000u)};
;                     if (br < 2) { const u32x4 b = gb[m][bj]; const float d[8] = {clampg(b.x << 16), clampg(b.x & 0xffff0000u), clampg(b.y << 16), clampg(b.y & 0xffff0000u), clampg(b.z << 16), clampg(b.z & 0xffff0000u), clampg(b.w << 16), clampg(b.w & 0xffff0000u)};
; #pragma unroll
;                         for (int e = 0; e < 8; ++e) f[e] *= __builtin_amdgcn_rcpf(d[e]); }
;                     f32x4 x0 = acc[ai][bj][m][0], x1 = acc[ai][bj][m][1];
;                     x0[0] *= f[0]; x0[1] *= f[1]; x0[2] *= f[2]; x0[3] *= f[3]; x1[0] *= f[4]; x1[1] *= f[5]; x1[2] *= f[6]; x1[3] *= f[7];
;                     if (br < 2) { acc[ai][bj][m][0] = x0; acc[ai][bj][m][1] = x1; }
;                     else *(u32x4*)(O + (size_t)(ai * HALF + m * 16) * D + HALF * bj) = pack8(x0, x1);
.LBB0_615:
	v_pk_mul_f32 v[118:119], v[118:119], v[188:189]
	v_pk_mul_f32 v[120:121], v[120:121], v[186:187]
	v_pk_mul_f32 v[114:115], v[114:115], v[190:191]
	s_and_b64 vcc, exec, s[6:7]
	v_pk_mul_f32 v[116:117], v[116:117], v[182:183]
	s_cbranch_vccnz .LBB0_617
	v_cvt_pk_bf16_f32 v184, v118, v119
	v_cvt_pk_bf16_f32 v185, v120, v121
	v_cvt_pk_bf16_f32 v187, v116, v117
	v_add_co_u32_e32 v182, vcc, 0x8000, v196
	v_cvt_pk_bf16_f32 v186, v114, v115
	s_nop 0
	v_addc_co_u32_e32 v183, vcc, 0, v197, vcc
	global_store_dwordx4 v[182:183], v[184:187], off
	s_branch .LBB0_618
.LBB0_617:
.LBB0_618:
	s_and_b64 vcc, exec, s[4:5]
	s_cbranch_vccnz .Lp3g_2
	v_add_co_u32_e32 v244, vcc, 0x48000, v198
	s_nop 1
	v_addc_co_u32_e32 v245, vcc, 0, v199, vcc
	global_load_dwordx4 v[150:153], v[244:245], off

; __device__ __forceinline__ u32x4 pack8(const f32x4 a, const f32x4 b) { u32x4 w; w.x = cvt_pk_bf16(a[0], a[1]); w.y = cvt_pk_bf16(a[2], a[3]); w.z = cvt_pk_bf16(b[0], b[1]); w.w = cvt_pk_bf16(b[2], b[3]); return w; }
; __device__ __forceinline__ float clampg(unsigned bits) { return __uint_as_float(bits > 0x0da24260u ? bits : 0x0da24260u); }
;     __device__ __forceinline__ void operator()(acc_t& acc, const Unit& u, int wr, int wc, int fr, int fq) const {
;     ...
;             for (int m = 0; m < 4; ++m)
; #pragma unroll
;                 for (int bj = 0; bj < 2; ++bj) {
;                     const u32x4 a = ga[m][bj]; float f[8] = {clampg(a.x << 16), clampg(a.x & 0xffff0000u), clampg(a.y << 16), clampg(a.y & 0xffff0000u), clampg(a.z << 16), clampg(a.z & 0xffff0000u), clampg(a.w << 16), clampg(a.w & 0xffff0000u)};
;                     if (br < 2) { const u32x4 b = gb[m][bj]; const float d[8] = {clampg(b.x << 16), clampg(b.x & 0xffff0000u), clampg(b.y << 16), clampg(b.y & 0xffff0000u), clampg(b.z << 16), clampg(b.z & 0xffff0000u), clampg(b.w << 16), clampg(b.w & 0xffff0000u)};
; #pragma unroll
;                         for (int e = 0; e < 8; ++e) f[e] *= __builtin_amdgcn_rcpf(d[e]); }
;                     f32x4 x0 = acc[ai][bj][m][0], x1 = acc[ai][bj][m][1];
;                     x0[0] *= f[0]; x0[1] *= f[1]; x0[2] *= f[2]; x0[3] *= f[3]; x1[0] *= f[4]; x1[1] *= f[5]; x1[2] *= f[6]; x1[3] *= f[7];
;                     if (br < 2) { acc[ai][bj][m][0] = x0; acc[ai][bj][m][1] = x1; }
;                     else *(u32x4*)(O + (size_t)(ai * HALF + m * 16) * D + HALF * bj) = pack8(x0, x1);
.LBB0_622:
	v_pk_mul_f32 v[86:87], v[86:87], v[184:185]
	v_pk_mul_f32 v[88:89], v[88:89], v[182:183]
	v_pk_mul_f32 v[82:83], v[82:83], v[186:187]
	s_and_b64 vcc, exec, s[6:7]
	v_pk_mul_f32 v[84:85], v[84:85], v[178:179]
	s_cbranch_vccnz .LBB0_624
	v_cvt_pk_bf16_f32 v180, v86, v87
	v_cvt_pk_bf16_f32 v181, v88, v89
	v_cvt_pk_bf16_f32 v183, v84, v85
	v_add_co_u32_e32 v178, vcc, 0x8000, v196
	v_cvt_pk_bf16_f32 v182, v82, v83
	s_nop 0
	v_addc_co_u32_e32 v179, vcc, 0, v197, vcc
	global_store_dwordx4 v[178:179], v[180:183], off offset:256
	s_branch .LBB0_625
.LBB0_624:
.LBB0_625:
	s_and_b64 vcc, exec, s[4:5]
	s_cbranch_vccnz .Lp3g_3
	v_add_co_u32_e32 v244, vcc, 0x48000, v198
	s_nop 1
	v_addc_co_u32_e32 v245, vcc, 0, v199, vcc
	global_load_dwordx4 v[146:149], v[244:245], off offset:256

; __device__ __forceinline__ u32x4 pack8(const f32x4 a, const f32x4 b) { u32x4 w; w.x = cvt_pk_bf16(a[0], a[1]); w.y = cvt_pk_bf16(a[2], a[3]); w.z = cvt_pk_bf16(b[0], b[1]); w.w = cvt_pk_bf16(b[2], b[3]); return w; }
; __device__ __forceinline__ float clampg(unsigned bits) { return __uint_as_float(bits > 0x0da24260u ? bits : 0x0da24260u); }
;     __device__ __forceinline__ void operator()(acc_t& acc, const Unit& u, int wr, int wc, int fr, int fq) const {
;     ...
;             for (int m = 0; m < 4; ++m)
; #pragma unroll
;                 for (int bj = 0; bj < 2; ++bj) {
;                     const u32x4 a = ga[m][bj]; float f[8] = {clampg(a.x << 16), clampg(a.x & 0xffff0000u), clampg(a.y << 16), clampg(a.y & 0xffff0000u), clampg(a.z << 16), clampg(a.z & 0xffff0000u), clampg(a.w << 16), clampg(a.w & 0xffff0000u)};
;                     if (br < 2) { const u32x4 b = gb[m][bj]; const float d[8] = {clampg(b.x << 16), clampg(b.x & 0xffff0000u), clampg(b.y << 16), clampg(b.y & 0xffff0000u), clampg(b.z << 16), clampg(b.z & 0xffff0000u), clampg(b.w << 16), clampg(b.w & 0xffff0000u)};
; #pragma unroll
;                         for (int e = 0; e < 8; ++e) f[e] *= __builtin_amdgcn_rcpf(d[e]); }
;                     f32x4 x0 = acc[ai][bj][m][0], x1 = acc[ai][bj][m][1];
;                     x0[0] *= f[0]; x0[1] *= f[1]; x0[2] *= f[2]; x0[3] *= f[3]; x1[0] *= f[4]; x1[1] *= f[5]; x1[2] *= f[6]; x1[3] *= f[7];
;                     if (br < 2) { acc[ai][bj][m][0] = x0; acc[ai][bj][m][1] = x1; }
;                     else *(u32x4*)(O + (size_t)(ai * HALF + m * 16) * D + HALF * bj) = pack8(x0, x1);
.LBB0_629:
	v_pk_mul_f32 v[110:111], v[110:111], v[180:181]
	v_pk_mul_f32 v[112:113], v[112:113], v[178:179]
	v_pk_mul_f32 v[106:107], v[106:107], v[182:183]
	s_and_b64 vcc, exec, s[6:7]
	v_pk_mul_f32 v[108:109], v[108:109], v[174:175]
	s_cbranch_vccnz .LBB0_631
	v_cvt_pk_bf16_f32 v176, v110, v111
	v_cvt_pk_bf16_f32 v177, v112, v113
	v_cvt_pk_bf16_f32 v179, v108, v109
	v_add_co_u32_e32 v174, vcc, 0x10000, v196
	v_cvt_pk_bf16_f32 v178, v106, v107
	s_nop 0
	v_addc_co_u32_e32 v175, vcc, 0, v197, vcc
	global_store_dwordx4 v[174:175], v[176:179], off
	s_branch .LBB0_632
.LBB0_631:
.LBB0_632:
	s_and_b64 vcc, exec, s[4:5]
	s_cbranch_vccnz .Lp3g_4
	v_add_co_u32_e32 v244, vcc, 0x50000, v198
	s_nop 1
	v_addc_co_u32_e32 v245, vcc, 0, v199, vcc
	global_load_dwordx4 v[142:145], v[244:245], off

; __device__ __forceinline__ u32x4 pack8(const f32x4 a, const f32x4 b) { u32x4 w; w.x = cvt_pk_bf16(a[0], a[1]); w.y = cvt_pk_bf16(a[2], a[3]); w.z = cvt_pk_bf16(b[0], b[1]); w.w = cvt_pk_bf16(b[2], b[3]); return w; }
; __device__ __forceinline__ float clampg(unsigned bits) { return __uint_as_float(bits > 0x0da24260u ? bits : 0x0da24260u); }
;     __device__ __forceinline__ void operator()(acc_t& acc, const Unit& u, int wr, int wc, int fr, int fq) const {
;     ...
;             for (int m = 0; m < 4; ++m)
; #pragma unroll
;                 for (int bj = 0; bj < 2; ++bj) {
;                     const u32x4 a = ga[m][bj]; float f[8] = {clampg(a.x << 16), clampg(a.x & 0xffff0000u), clampg(a.y << 16), clampg(a.y & 0xffff0000u), clampg(a.z << 16), clampg(a.z & 0xffff0000u), clampg(a.w << 16), clampg(a.w & 0xffff0000u)};
;                     if (br < 2) { const u32x4 b = gb[m][bj]; const float d[8] = {clampg(b.x << 16), clampg(b.x & 0xffff0000u), clampg(b.y << 16), clampg(b.y & 0xffff0000u), clampg(b.z << 16), clampg(b.z & 0xffff0000u), clampg(b.w << 16), clampg(b.w & 0xffff0000u)};
; #pragma unroll
;                         for (int e = 0; e < 8; ++e) f[e] *= __builtin_amdgcn_rcpf(d[e]); }
;                     f32x4 x0 = acc[ai][bj][m][0], x1 = acc[ai][bj][m][1];
;                     x0[0] *= f[0]; x0[1] *= f[1]; x0[2] *= f[2]; x0[3] *= f[3]; x1[0] *= f[4]; x1[1] *= f[5]; x1[2] *= f[6]; x1[3] *= f[7];
;                     if (br < 2) { acc[ai][bj][m][0] = x0; acc[ai][bj][m][1] = x1; }
;                     else *(u32x4*)(O + (size_t)(ai * HALF + m * 16) * D + HALF * bj) = pack8(x0, x1);
.LBB0_636:
	v_pk_mul_f32 v[78:79], v[78:79], v[176:177]
	v_pk_mul_f32 v[80:81], v[80:81], v[174:175]
	v_pk_mul_f32 v[74:75], v[74:75], v[178:179]
	s_and_b64 vcc, exec, s[6:7]
	v_pk_mul_f32 v[76:77], v[76:77], v[170:171]
	s_cbranch_vccnz .LBB0_638
	v_cvt_pk_bf16_f32 v172, v78, v79
	v_cvt_pk_bf16_f32 v173, v80, v81
	v_cvt_pk_bf16_f32 v175, v76, v77
	v_add_co_u32_e32 v170, vcc, 0x10000, v196
	v_cvt_pk_bf16_f32 v174, v74, v75
	s_nop 0
	v_addc_co_u32_e32 v171, vcc, 0, v197, vcc
	global_store_dwordx4 v[170:171], v[172:175], off offset:256
	s_branch .LBB0_639
.LBB0_638:
.LBB0_639:
	s_and_b64 vcc, exec, s[4:5]
	s_cbranch_vccnz .Lp3g_5
	v_add_co_u32_e32 v244, vcc, 0x50000, v198
	s_nop 1
	v_addc_co_u32_e32 v245, vcc, 0, v199, vcc
	global_load_dwordx4 v[138:141], v[244:245], off offset:256

; __device__ __forceinline__ u32x4 pack8(const f32x4 a, const f32x4 b) { u32x4 w; w.x = cvt_pk_bf16(a[0], a[1]); w.y = cvt_pk_bf16(a[2], a[3]); w.z = cvt_pk_bf16(b[0], b[1]); w.w = cvt_pk_bf16(b[2], b[3]); return w; }
; __device__ __forceinline__ float clampg(unsigned bits) { return __uint_as_float(bits > 0x0da24260u ? bits : 0x0da24260u); }
;     __device__ __forceinline__ void operator()(acc_t& acc, const Unit& u, int wr, int wc, int fr, int fq) const {
;     ...
;             for (int m = 0; m < 4; ++m)
; #pragma unroll
;                 for (int bj = 0; bj < 2; ++bj) {
;                     const u32x4 a = ga[m][bj]; float f[8] = {clampg(a.x << 16), clampg(a.x & 0xffff0000u), clampg(a.y << 16), clampg(a.y & 0xffff0000u), clampg(a.z << 16), clampg(a.z & 0xffff0000u), clampg(a.w << 16), clampg(a.w & 0xffff0000u)};
;                     if (br < 2) { const u32x4 b = gb[m][bj]; const float d[8] = {clampg(b.x << 16), clampg(b.x & 0xffff0000u), clampg(b.y << 16), clampg(b.y & 0xffff0000u), clampg(b.z << 16), clampg(b.z & 0xffff0000u), clampg(b.w << 16), clampg(b.w & 0xffff0000u)};
; #pragma unroll
;                         for (int e = 0; e < 8; ++e) f[e] *= __builtin_amdgcn_rcpf(d[e]); }
;                     f32x4 x0 = acc[ai][bj][m][0], x1 = acc[ai][bj][m][1];
;                     x0[0] *= f[0]; x0[1] *= f[1]; x0[2] *= f[2]; x0[3] *= f[3]; x1[0] *= f[4]; x1[1] *= f[5]; x1[2] *= f[6]; x1[3] *= f[7];
;                     if (br < 2) { acc[ai][bj][m][0] = x0; acc[ai][bj][m][1] = x1; }
;                     else *(u32x4*)(O + (size_t)(ai * HALF + m * 16) * D + HALF * bj) = pack8(x0, x1);
.LBB0_643:
	v_pk_mul_f32 v[102:103], v[102:103], v[172:173]
	v_pk_mul_f32 v[104:105], v[104:105], v[170:171]
	v_pk_mul_f32 v[98:99], v[98:99], v[174:175]
	s_and_b64 vcc, exec, s[6:7]
	v_pk_mul_f32 v[100:101], v[100:101], v[166:167]
	s_cbranch_vccnz .LBB0_645
	v_cvt_pk_bf16_f32 v168, v102, v103
	v_cvt_pk_bf16_f32 v169, v104, v105
	v_cvt_pk_bf16_f32 v171, v100, v101
	v_add_co_u32_e32 v166, vcc, 0x18000, v196
	v_cvt_pk_bf16_f32 v170, v98, v99
	s_nop 0
	v_addc_co_u32_e32 v167, vcc, 0, v197, vcc
	global_store_dwordx4 v[166:167], v[168:171], off
	s_branch .LBB0_646
.LBB0_645:
.LBB0_646:
	s_and_b64 vcc, exec, s[64:65]
	s_cbranch_vccnz .Lp3w7_a
	s_waitcnt vmcnt(6)
	s_branch .Lp3w7_b

; __device__ __forceinline__ u32x4 pack8(const f32x4 a, const f32x4 b) { u32x4 w; w.x = cvt_pk_bf16(a[0], a[1]); w.y = cvt_pk_bf16(a[2], a[3]); w.z = cvt_pk_bf16(b[0], b[1]); w.w = cvt_pk_bf16(b[2], b[3]); return w; }
; __device__ __forceinline__ float clampg(unsigned bits) { return __uint_as_float(bits > 0x0da24260u ? bits : 0x0da24260u); }
;     __device__ __forceinline__ void operator()(acc_t& acc, const Unit& u, int wr, int wc, int fr, int fq) const {
;     ...
;             for (int m = 0; m < 4; ++m)
; #pragma unroll
;                 for (int bj = 0; bj < 2; ++bj) {
;                     const u32x4 a = ga[m][bj]; float f[8] = {clampg(a.x << 16), clampg(a.x & 0xffff0000u), clampg(a.y << 16), clampg(a.y & 0xffff0000u), clampg(a.z << 16), clampg(a.z & 0xffff0000u), clampg(a.w << 16), clampg(a.w & 0xffff0000u)};
;                     if (br < 2) { const u32x4 b = gb[m][bj]; const float d[8] = {clampg(b.x << 16), clampg(b.x & 0xffff0000u), clampg(b.y << 16), clampg(b.y & 0xffff0000u), clampg(b.z << 16), clampg(b.z & 0xffff0000u), clampg(b.w << 16), clampg(b.w & 0xffff0000u)};
; #pragma unroll
;                         for (int e = 0; e < 8; ++e) f[e] *= __builtin_amdgcn_rcpf(d[e]); }
;                     f32x4 x0 = acc[ai][bj][m][0], x1 = acc[ai][bj][m][1];
;                     x0[0] *= f[0]; x0[1] *= f[1]; x0[2] *= f[2]; x0[3] *= f[3]; x1[0] *= f[4]; x1[1] *= f[5]; x1[2] *= f[6]; x1[3] *= f[7];
;                     if (br < 2) { acc[ai][bj][m][0] = x0; acc[ai][bj][m][1] = x1; }
;                     else *(u32x4*)(O + (size_t)(ai * HALF + m * 16) * D + HALF * bj) = pack8(x0, x1);
.LBB0_650:
	v_pk_mul_f32 v[70:71], v[70:71], v[168:169]
	v_pk_mul_f32 v[72:73], v[72:73], v[166:167]
	v_pk_mul_f32 v[62:63], v[62:63], v[170:171]
	s_and_b64 vcc, exec, s[6:7]
	v_pk_mul_f32 v[64:65], v[64:65], v[162:163]
	s_cbranch_vccnz .LBB0_652
	v_cvt_pk_bf16_f32 v164, v70, v71
	v_cvt_pk_bf16_f32 v165, v72, v73
	v_cvt_pk_bf16_f32 v167, v64, v65
	v_add_co_u32_e32 v162, vcc, 0x18000, v196
	v_cvt_pk_bf16_f32 v166, v62, v63
	s_nop 0
	v_addc_co_u32_e32 v163, vcc, 0, v197, vcc
	global_store_dwordx4 v[162:163], v[164:167], off offset:256
	s_branch .LBB0_653
.LBB0_652:
.LBB0_653:
	s_and_b64 vcc, exec, s[64:65]
	s_cbranch_vccz .Lp3t_skipa
	v_add_co_u32_e32 v244, vcc, 0x58000, v200
	s_nop 1
	v_addc_co_u32_e32 v245, vcc, 0, v201, vcc
	global_load_dwordx4 v[248:251], v[244:245], off nt

; __device__ __forceinline__ u32x4 pack8(const f32x4 a, const f32x4 b) { u32x4 w; w.x = cvt_pk_bf16(a[0], a[1]); w.y = cvt_pk_bf16(a[2], a[3]); w.z = cvt_pk_bf16(b[0], b[1]); w.w = cvt_pk_bf16(b[2], b[3]); return w; }
; __device__ __forceinline__ float clampg(unsigned bits) { return __uint_as_float(bits > 0x0da24260u ? bits : 0x0da24260u); }
;     __device__ __forceinline__ void operator()(acc_t& acc, const Unit& u, int wr, int wc, int fr, int fq) const {
;     ...
;                     const u32x4 a = ga[m][bj]; float f[8] = {clampg(a.x << 16), clampg(a.x & 0xffff0000u), clampg(a.y << 16), clampg(a.y & 0xffff0000u), clampg(a.z << 16), clampg(a.z & 0xffff0000u), clampg(a.w << 16), clampg(a.w & 0xffff0000u)};
;                     if (br < 2) { const u32x4 b = gb[m][bj]; const float d[8] = {clampg(b.x << 16), clampg(b.x & 0xffff0000u), clampg(b.y << 16), clampg(b.y & 0xffff0000u), clampg(b.z << 16), clampg(b.z & 0xffff0000u), clampg(b.w << 16), clampg(b.w & 0xffff0000u)};
; #pragma unroll
;                         for (int e = 0; e < 8; ++e) f[e] *= __builtin_amdgcn_rcpf(d[e]); }
;                     f32x4 x0 = acc[ai][bj][m][0], x1 = acc[ai][bj][m][1];
;                     x0[0] *= f[0]; x0[1] *= f[1]; x0[2] *= f[2]; x0[3] *= f[3]; x1[0] *= f[4]; x1[1] *= f[5]; x1[2] *= f[6]; x1[3] *= f[7];
;                     if (br < 2) { acc[ai][bj][m][0] = x0; acc[ai][bj][m][1] = x1; }
;                     else *(u32x4*)(O + (size_t)(ai * HALF + m * 16) * D + HALF * bj) = pack8(x0, x1);
.LBB0_673:
	v_pk_mul_f32 v[66:67], v[66:67], v[200:201]
	v_pk_mul_f32 v[68:69], v[68:69], v[198:199]
	v_pk_mul_f32 v[58:59], v[58:59], v[202:203]
	s_and_b64 vcc, exec, s[6:7]
	v_pk_mul_f32 v[60:61], v[60:61], v[190:191]
	s_cbranch_vccnz .LBB0_675
	v_cvt_pk_bf16_f32 v158, v66, v67
	v_cvt_pk_bf16_f32 v159, v68, v69
	v_cvt_pk_bf16_f32 v161, v60, v61
	v_add_co_u32_e32 v190, vcc, 0x40000, v196
	v_cvt_pk_bf16_f32 v160, v58, v59
	s_nop 0
	v_addc_co_u32_e32 v191, vcc, 0, v197, vcc
	global_store_dwordx4 v[190:191], v[158:161], off
	s_branch .LBB0_676
.LBB0_675:
.LBB0_676:
	s_waitcnt vmcnt(6)
	v_lshlrev_b32_e32 v158, 16, v224
	v_max_u32_e32 v190, 0xda24260, v158
	v_and_b32_e32 v158, 0xffff0000, v224
	v_max_u32_e32 v191, 0xda24260, v158
	v_lshlrev_b32_e32 v158, 16, v225
	v_max_u32_e32 v160, 0xda24260, v158
	v_and_b32_e32 v158, 0xffff0000, v225
	v_max_u32_e32 v161, 0xda24260, v158
	v_lshlrev_b32_e32 v158, 16, v226
	v_max_u32_e32 v186, 0xda24260, v158
	v_and_b32_e32 v158, 0xffff0000, v226
	v_max_u32_e32 v187, 0xda24260, v158
	v_lshlrev_b32_e32 v158, 16, v227
	v_and_b32_e32 v159, 0xffff0000, v227
	v_mov_b32_e32 v224, v154
	v_mov_b32_e32 v225, v155
	v_mov_b32_e32 v226, v156
	v_mov_b32_e32 v227, v157
	v_max_u32_e32 v158, 0xda24260, v158
	v_max_u32_e32 v159, 0xda24260, v159
	s_and_b64 vcc, exec, s[6:7]
	s_mov_b64 s[2:3], -1
	s_cbranch_vccnz .LBB0_678
	s_mov_b64 s[2:3], 0

; __device__ __forceinline__ u32x4 pack8(const f32x4 a, const f32x4 b) { u32x4 w; w.x = cvt_pk_bf16(a[0], a[1]); w.y = cvt_pk_bf16(a[2], a[3]); w.z = cvt_pk_bf16(b[0], b[1]); w.w = cvt_pk_bf16(b[2], b[3]); return w; }
; __device__ __forceinline__ float clampg(unsigned bits) { return __uint_as_float(bits > 0x0da24260u ? bits : 0x0da24260u); }
;     __device__ __forceinline__ void operator()(acc_t& acc, const Unit& u, int wr, int wc, int fr, int fq) const {
;     ...
;                     const u32x4 a = ga[m][bj]; float f[8] = {clampg(a.x << 16), clampg(a.x & 0xffff0000u), clampg(a.y << 16), clampg(a.y & 0xffff0000u), clampg(a.z << 16), clampg(a.z & 0xffff0000u), clampg(a.w << 16), clampg(a.w & 0xffff0000u)};
;                     if (br < 2) { const u32x4 b = gb[m][bj]; const float d[8] = {clampg(b.x << 16), clampg(b.x & 0xffff0000u), clampg(b.y << 16), clampg(b.y & 0xffff0000u), clampg(b.z << 16), clampg(b.z & 0xffff0000u), clampg(b.w << 16), clampg(b.w & 0xffff0000u)};
; #pragma unroll
;                         for (int e = 0; e < 8; ++e) f[e] *= __builtin_amdgcn_rcpf(d[e]); }
;                     f32x4 x0 = acc[ai][bj][m][0], x1 = acc[ai][bj][m][1];
;                     x0[0] *= f[0]; x0[1] *= f[1]; x0[2] *= f[2]; x0[3] *= f[3]; x1[0] *= f[4]; x1[1] *= f[5]; x1[2] *= f[6]; x1[3] *= f[7];
;                     if (br < 2) { acc[ai][bj][m][0] = x0; acc[ai][bj][m][1] = x1; }
;                     else *(u32x4*)(O + (size_t)(ai * HALF + m * 16) * D + HALF * bj) = pack8(x0, x1);
.LBB0_680:
	v_pk_mul_f32 v[30:31], v[30:31], v[190:191]
	v_pk_mul_f32 v[32:33], v[32:33], v[160:161]
	v_pk_mul_f32 v[26:27], v[26:27], v[186:187]
	s_and_b64 vcc, exec, s[6:7]
	v_pk_mul_f32 v[28:29], v[28:29], v[158:159]
	s_cbranch_vccnz .LBB0_682
	v_cvt_pk_bf16_f32 v154, v30, v31
	v_cvt_pk_bf16_f32 v155, v32, v33
	v_cvt_pk_bf16_f32 v157, v28, v29
	v_add_co_u32_e32 v158, vcc, 0x40000, v196
	v_cvt_pk_bf16_f32 v156, v26, v27
	s_nop 0
	v_addc_co_u32_e32 v159, vcc, 0, v197, vcc
	global_store_dwordx4 v[158:159], v[154:157], off offset:256
	s_branch .LBB0_683
.LBB0_682:
.LBB0_683:
	s_waitcnt vmcnt(5)
	v_lshlrev_b32_e32 v154, 16, v228
	v_max_u32_e32 v158, 0xda24260, v154
	v_and_b32_e32 v154, 0xffff0000, v228
	v_max_u32_e32 v159, 0xda24260, v154
	v_lshlrev_b32_e32 v154, 16, v229
	v_max_u32_e32 v156, 0xda24260, v154
	v_and_b32_e32 v154, 0xffff0000, v229
	v_max_u32_e32 v157, 0xda24260, v154
	v_lshlrev_b32_e32 v154, 16, v230
	v_max_u32_e32 v160, 0xda24260, v154
	v_and_b32_e32 v154, 0xffff0000, v230
	v_max_u32_e32 v161, 0xda24260, v154
	v_lshlrev_b32_e32 v154, 16, v231
	v_and_b32_e32 v155, 0xffff0000, v231
	v_mov_b32_e32 v228, v150
	v_mov_b32_e32 v229, v151
	v_mov_b32_e32 v230, v152
	v_mov_b32_e32 v231, v153
	v_max_u32_e32 v154, 0xda24260, v154
	v_max_u32_e32 v155, 0xda24260, v155
	s_and_b64 vcc, exec, s[6:7]
	s_mov_b64 s[2:3], -1
	s_cbranch_vccnz .LBB0_685
	s_mov_b64 s[2:3], 0

; __device__ __forceinline__ u32x4 pack8(const f32x4 a, const f32x4 b) { u32x4 w; w.x = cvt_pk_bf16(a[0], a[1]); w.y = cvt_pk_bf16(a[2], a[3]); w.z = cvt_pk_bf16(b[0], b[1]); w.w = cvt_pk_bf16(b[2], b[3]); return w; }
; __device__ __forceinline__ float clampg(unsigned bits) { return __uint_as_float(bits > 0x0da24260u ? bits : 0x0da24260u); }
;     __device__ __forceinline__ void operator()(acc_t& acc, const Unit& u, int wr, int wc, int fr, int fq) const {
;     ...
;                     const u32x4 a = ga[m][bj]; float f[8] = {clampg(a.x << 16), clampg(a.x & 0xffff0000u), clampg(a.y << 16), clampg(a.y & 0xffff0000u), clampg(a.z << 16), clampg(a.z & 0xffff0000u), clampg(a.w << 16), clampg(a.w & 0xffff0000u)};
;                     if (br < 2) { const u32x4 b = gb[m][bj]; const float d[8] = {clampg(b.x << 16), clampg(b.x & 0xffff0000u), clampg(b.y << 16), clampg(b.y & 0xffff0000u), clampg(b.z << 16), clampg(b.z & 0xffff0000u), clampg(b.w << 16), clampg(b.w & 0xffff0000u)};
; #pragma unroll
;                         for (int e = 0; e < 8; ++e) f[e] *= __builtin_amdgcn_rcpf(d[e]); }
;                     f32x4 x0 = acc[ai][bj][m][0], x1 = acc[ai][bj][m][1];
;                     x0[0] *= f[0]; x0[1] *= f[1]; x0[2] *= f[2]; x0[3] *= f[3]; x1[0] *= f[4]; x1[1] *= f[5]; x1[2] *= f[6]; x1[3] *= f[7];
;                     if (br < 2) { acc[ai][bj][m][0] = x0; acc[ai][bj][m][1] = x1; }
;                     else *(u32x4*)(O + (size_t)(ai * HALF + m * 16) * D + HALF * bj) = pack8(x0, x1);
.LBB0_687:
	v_pk_mul_f32 v[54:55], v[54:55], v[158:159]
	v_pk_mul_f32 v[56:57], v[56:57], v[156:157]
	v_pk_mul_f32 v[50:51], v[50:51], v[160:161]
	s_and_b64 vcc, exec, s[6:7]
	v_pk_mul_f32 v[52:53], v[52:53], v[154:155]
	s_cbranch_vccnz .LBB0_689
	v_cvt_pk_bf16_f32 v150, v54, v55
	v_cvt_pk_bf16_f32 v151, v56, v57
	v_cvt_pk_bf16_f32 v153, v52, v53
	v_add_co_u32_e32 v154, vcc, 0x48000, v196
	v_cvt_pk_bf16_f32 v152, v50, v51
	s_nop 0
	v_addc_co_u32_e32 v155, vcc, 0, v197, vcc
	global_store_dwordx4 v[154:155], v[150:153], off
	s_branch .LBB0_690
.LBB0_689:
.LBB0_690:
	s_waitcnt vmcnt(4)
	v_lshlrev_b32_e32 v150, 16, v232
	v_max_u32_e32 v154, 0xda24260, v150
	v_and_b32_e32 v150, 0xffff0000, v232
	v_max_u32_e32 v155, 0xda24260, v150
	v_lshlrev_b32_e32 v150, 16, v233
	v_max_u32_e32 v152, 0xda24260, v150
	v_and_b32_e32 v150, 0xffff0000, v233
	v_max_u32_e32 v153, 0xda24260, v150
	v_lshlrev_b32_e32 v150, 16, v234
	v_max_u32_e32 v156, 0xda24260, v150
	v_and_b32_e32 v150, 0xffff0000, v234
	v_max_u32_e32 v157, 0xda24260, v150
	v_lshlrev_b32_e32 v150, 16, v235
	v_and_b32_e32 v151, 0xffff0000, v235
	v_mov_b32_e32 v232, v146
	v_mov_b32_e32 v233, v147
	v_mov_b32_e32 v234, v148
	v_mov_b32_e32 v235, v149
	v_max_u32_e32 v150, 0xda24260, v150
	v_max_u32_e32 v151, 0xda24260, v151
	s_and_b64 vcc, exec, s[6:7]
	s_mov_b64 s[2:3], -1
	s_cbranch_vccnz .LBB0_692
	s_mov_b64 s[2:3], 0

; __device__ __forceinline__ u32x4 pack8(const f32x4 a, const f32x4 b) { u32x4 w; w.x = cvt_pk_bf16(a[0], a[1]); w.y = cvt_pk_bf16(a[2], a[3]); w.z = cvt_pk_bf16(b[0], b[1]); w.w = cvt_pk_bf16(b[2], b[3]); return w; }
; __device__ __forceinline__ float clampg(unsigned bits) { return __uint_as_float(bits > 0x0da24260u ? bits : 0x0da24260u); }
;     __device__ __forceinline__ void operator()(acc_t& acc, const Unit& u, int wr, int wc, int fr, int fq) const {
;     ...
;                     const u32x4 a = ga[m][bj]; float f[8] = {clampg(a.x << 16), clampg(a.x & 0xffff0000u), clampg(a.y << 16), clampg(a.y & 0xffff0000u), clampg(a.z << 16), clampg(a.z & 0xffff0000u), clampg(a.w << 16), clampg(a.w & 0xffff0000u)};
;                     if (br < 2) { const u32x4 b = gb[m][bj]; const float d[8] = {clampg(b.x << 16), clampg(b.x & 0xffff0000u), clampg(b.y << 16), clampg(b.y & 0xffff0000u), clampg(b.z << 16), clampg(b.z & 0xffff0000u), clampg(b.w << 16), clampg(b.w & 0xffff0000u)};
; #pragma unroll
;                         for (int e = 0; e < 8; ++e) f[e] *= __builtin_amdgcn_rcpf(d[e]); }
;                     f32x4 x0 = acc[ai][bj][m][0], x1 = acc[ai][bj][m][1];
;                     x0[0] *= f[0]; x0[1] *= f[1]; x0[2] *= f[2]; x0[3] *= f[3]; x1[0] *= f[4]; x1[1] *= f[5]; x1[2] *= f[6]; x1[3] *= f[7];
;                     if (br < 2) { acc[ai][bj][m][0] = x0; acc[ai][bj][m][1] = x1; }
;                     else *(u32x4*)(O + (size_t)(ai * HALF + m * 16) * D + HALF * bj) = pack8(x0, x1);
.LBB0_694:
	v_pk_mul_f32 v[22:23], v[22:23], v[154:155]
	v_pk_mul_f32 v[24:25], v[24:25], v[152:153]
	v_pk_mul_f32 v[18:19], v[18:19], v[156:157]
	s_and_b64 vcc, exec, s[6:7]
	v_pk_mul_f32 v[20:21], v[20:21], v[150:151]
	s_cbranch_vccnz .LBB0_696
	v_cvt_pk_bf16_f32 v146, v22, v23
	v_cvt_pk_bf16_f32 v147, v24, v25
	v_cvt_pk_bf16_f32 v149, v20, v21
	v_add_co_u32_e32 v150, vcc, 0x48000, v196
	v_cvt_pk_bf16_f32 v148, v18, v19
	s_nop 0
	v_addc_co_u32_e32 v151, vcc, 0, v197, vcc
	global_store_dwordx4 v[150:151], v[146:149], off offset:256
	s_branch .LBB0_697
.LBB0_696:
.LBB0_697:
	s_waitcnt vmcnt(3)
	v_lshlrev_b32_e32 v146, 16, v236
	v_max_u32_e32 v150, 0xda24260, v146
	v_and_b32_e32 v146, 0xffff0000, v236
	v_max_u32_e32 v151, 0xda24260, v146
	v_lshlrev_b32_e32 v146, 16, v237
	v_max_u32_e32 v148, 0xda24260, v146
	v_and_b32_e32 v146, 0xffff0000, v237
	v_max_u32_e32 v149, 0xda24260, v146
	v_lshlrev_b32_e32 v146, 16, v238
	v_max_u32_e32 v152, 0xda24260, v146
	v_and_b32_e32 v146, 0xffff0000, v238
	v_max_u32_e32 v153, 0xda24260, v146
	v_lshlrev_b32_e32 v146, 16, v239
	v_and_b32_e32 v147, 0xffff0000, v239
	v_mov_b32_e32 v236, v142
	v_mov_b32_e32 v237, v143
	v_mov_b32_e32 v238, v144
	v_mov_b32_e32 v239, v145
	v_max_u32_e32 v146, 0xda24260, v146
	v_max_u32_e32 v147, 0xda24260, v147
	s_and_b64 vcc, exec, s[6:7]
	s_mov_b64 s[2:3], -1
	s_cbranch_vccnz .LBB0_699
	s_mov_b64 s[2:3], 0

; __device__ __forceinline__ u32x4 pack8(const f32x4 a, const f32x4 b) { u32x4 w; w.x = cvt_pk_bf16(a[0], a[1]); w.y = cvt_pk_bf16(a[2], a[3]); w.z = cvt_pk_bf16(b[0], b[1]); w.w = cvt_pk_bf16(b[2], b[3]); return w; }
; __device__ __forceinline__ float clampg(unsigned bits) { return __uint_as_float(bits > 0x0da24260u ? bits : 0x0da24260u); }
;     __device__ __forceinline__ void operator()(acc_t& acc, const Unit& u, int wr, int wc, int fr, int fq) const {
;     ...
;                     const u32x4 a = ga[m][bj]; float f[8] = {clampg(a.x << 16), clampg(a.x & 0xffff0000u), clampg(a.y << 16), clampg(a.y & 0xffff0000u), clampg(a.z << 16), clampg(a.z & 0xffff0000u), clampg(a.w << 16), clampg(a.w & 0xffff0000u)};
;                     if (br < 2) { const u32x4 b = gb[m][bj]; const float d[8] = {clampg(b.x << 16), clampg(b.x & 0xffff0000u), clampg(b.y << 16), clampg(b.y & 0xffff0000u), clampg(b.z << 16), clampg(b.z & 0xffff0000u), clampg(b.w << 16), clampg(b.w & 0xffff0000u)};
; #pragma unroll
;                         for (int e = 0; e < 8; ++e) f[e] *= __builtin_amdgcn_rcpf(d[e]); }
;                     f32x4 x0 = acc[ai][bj][m][0], x1 = acc[ai][bj][m][1];
;                     x0[0] *= f[0]; x0[1] *= f[1]; x0[2] *= f[2]; x0[3] *= f[3]; x1[0] *= f[4]; x1[1] *= f[5]; x1[2] *= f[6]; x1[3] *= f[7];
;                     if (br < 2) { acc[ai][bj][m][0] = x0; acc[ai][bj][m][1] = x1; }
;                     else *(u32x4*)(O + (size_t)(ai * HALF + m * 16) * D + HALF * bj) = pack8(x0, x1);
.LBB0_701:
	v_pk_mul_f32 v[46:47], v[46:47], v[150:151]
	v_pk_mul_f32 v[48:49], v[48:49], v[148:149]
	v_pk_mul_f32 v[42:43], v[42:43], v[152:153]
	s_and_b64 vcc, exec, s[6:7]
	v_pk_mul_f32 v[44:45], v[44:45], v[146:147]
	s_cbranch_vccnz .LBB0_703
	v_cvt_pk_bf16_f32 v142, v46, v47
	v_cvt_pk_bf16_f32 v143, v48, v49
	v_cvt_pk_bf16_f32 v145, v44, v45
	v_add_co_u32_e32 v146, vcc, 0x50000, v196
	v_cvt_pk_bf16_f32 v144, v42, v43
	s_nop 0
	v_addc_co_u32_e32 v147, vcc, 0, v197, vcc
	global_store_dwordx4 v[146:147], v[142:145], off
	s_branch .LBB0_704
.LBB0_703:
.LBB0_704:
	s_waitcnt vmcnt(2)
	v_lshlrev_b32_e32 v142, 16, v240
	v_max_u32_e32 v146, 0xda24260, v142
	v_and_b32_e32 v142, 0xffff0000, v240
	v_max_u32_e32 v147, 0xda24260, v142
	v_lshlrev_b32_e32 v142, 16, v241
	v_max_u32_e32 v144, 0xda24260, v142
	v_and_b32_e32 v142, 0xffff0000, v241
	v_max_u32_e32 v145, 0xda24260, v142
	v_lshlrev_b32_e32 v142, 16, v242
	v_max_u32_e32 v148, 0xda24260, v142
	v_and_b32_e32 v142, 0xffff0000, v242
	v_max_u32_e32 v149, 0xda24260, v142
	v_lshlrev_b32_e32 v142, 16, v243
	v_and_b32_e32 v143, 0xffff0000, v243
	v_mov_b32_e32 v240, v138
	v_mov_b32_e32 v241, v139
	v_mov_b32_e32 v242, v140
	v_mov_b32_e32 v243, v141
	v_max_u32_e32 v142, 0xda24260, v142
	v_max_u32_e32 v143, 0xda24260, v143
	s_and_b64 vcc, exec, s[6:7]
	s_mov_b64 s[2:3], -1
	s_cbranch_vccnz .LBB0_706
	s_mov_b64 s[2:3], 0

; __device__ __forceinline__ u32x4 pack8(const f32x4 a, const f32x4 b) { u32x4 w; w.x = cvt_pk_bf16(a[0], a[1]); w.y = cvt_pk_bf16(a[2], a[3]); w.z = cvt_pk_bf16(b[0], b[1]); w.w = cvt_pk_bf16(b[2], b[3]); return w; }
; __device__ __forceinline__ float clampg(unsigned bits) { return __uint_as_float(bits > 0x0da24260u ? bits : 0x0da24260u); }
;     __device__ __forceinline__ void operator()(acc_t& acc, const Unit& u, int wr, int wc, int fr, int fq) const {
;     ...
;                     const u32x4 a = ga[m][bj]; float f[8] = {clampg(a.x << 16), clampg(a.x & 0xffff0000u), clampg(a.y << 16), clampg(a.y & 0xffff0000u), clampg(a.z << 16), clampg(a.z & 0xffff0000u), clampg(a.w << 16), clampg(a.w & 0xffff0000u)};
;                     if (br < 2) { const u32x4 b = gb[m][bj]; const float d[8] = {clampg(b.x << 16), clampg(b.x & 0xffff0000u), clampg(b.y << 16), clampg(b.y & 0xffff0000u), clampg(b.z << 16), clampg(b.z & 0xffff0000u), clampg(b.w << 16), clampg(b.w & 0xffff0000u)};
; #pragma unroll
;                         for (int e = 0; e < 8; ++e) f[e] *= __builtin_amdgcn_rcpf(d[e]); }
;                     f32x4 x0 = acc[ai][bj][m][0], x1 = acc[ai][bj][m][1];
;                     x0[0] *= f[0]; x0[1] *= f[1]; x0[2] *= f[2]; x0[3] *= f[3]; x1[0] *= f[4]; x1[1] *= f[5]; x1[2] *= f[6]; x1[3] *= f[7];
;                     if (br < 2) { acc[ai][bj][m][0] = x0; acc[ai][bj][m][1] = x1; }
;                     else *(u32x4*)(O + (size_t)(ai * HALF + m * 16) * D + HALF * bj) = pack8(x0, x1);
.LBB0_708:
	v_pk_mul_f32 v[14:15], v[14:15], v[146:147]
	v_pk_mul_f32 v[16:17], v[16:17], v[144:145]
	v_pk_mul_f32 v[10:11], v[10:11], v[148:149]
	s_and_b64 vcc, exec, s[6:7]
	v_pk_mul_f32 v[12:13], v[12:13], v[142:143]
	s_cbranch_vccnz .LBB0_710
	v_cvt_pk_bf16_f32 v138, v14, v15
	v_cvt_pk_bf16_f32 v139, v16, v17
	v_cvt_pk_bf16_f32 v141, v12, v13
	v_add_co_u32_e32 v142, vcc, 0x50000, v196
	v_cvt_pk_bf16_f32 v140, v10, v11
	s_nop 0
	v_addc_co_u32_e32 v143, vcc, 0, v197, vcc
	global_store_dwordx4 v[142:143], v[138:141], off offset:256
	s_branch .LBB0_711
.LBB0_710:
.LBB0_711:
	s_waitcnt vmcnt(1)
	v_lshlrev_b32_e32 v138, 16, v248
	v_max_u32_e32 v142, 0xda24260, v138
	v_and_b32_e32 v138, 0xffff0000, v248
	v_max_u32_e32 v143, 0xda24260, v138
	v_lshlrev_b32_e32 v138, 16, v249
	v_max_u32_e32 v140, 0xda24260, v138
	v_and_b32_e32 v138, 0xffff0000, v249
	v_max_u32_e32 v141, 0xda24260, v138
	v_lshlrev_b32_e32 v138, 16, v250
	v_max_u32_e32 v144, 0xda24260, v138
	v_and_b32_e32 v138, 0xffff0000, v250
	v_max_u32_e32 v145, 0xda24260, v138
	v_lshlrev_b32_e32 v138, 16, v251
	v_and_b32_e32 v139, 0xffff0000, v251
	v_mov_b32_e32 v248, v134
	v_mov_b32_e32 v249, v135
	v_mov_b32_e32 v250, v136
	v_mov_b32_e32 v251, v137
	v_max_u32_e32 v138, 0xda24260, v138
	v_max_u32_e32 v139, 0xda24260, v139
	s_and_b64 vcc, exec, s[6:7]
	s_mov_b64 s[2:3], -1
	s_cbranch_vccnz .LBB0_713
	s_mov_b64 s[2:3], 0

; __device__ __forceinline__ u32x4 pack8(const f32x4 a, const f32x4 b) { u32x4 w; w.x = cvt_pk_bf16(a[0], a[1]); w.y = cvt_pk_bf16(a[2], a[3]); w.z = cvt_pk_bf16(b[0], b[1]); w.w = cvt_pk_bf16(b[2], b[3]); return w; }
; __device__ __forceinline__ float clampg(unsigned bits) { return __uint_as_float(bits > 0x0da24260u ? bits : 0x0da24260u); }
;     __device__ __forceinline__ void operator()(acc_t& acc, const Unit& u, int wr, int wc, int fr, int fq) const {
;     ...
;                     const u32x4 a = ga[m][bj]; float f[8] = {clampg(a.x << 16), clampg(a.x & 0xffff0000u), clampg(a.y << 16), clampg(a.y & 0xffff0000u), clampg(a.z << 16), clampg(a.z & 0xffff0000u), clampg(a.w << 16), clampg(a.w & 0xffff0000u)};
;                     if (br < 2) { const u32x4 b = gb[m][bj]; const float d[8] = {clampg(b.x << 16), clampg(b.x & 0xffff0000u), clampg(b.y << 16), clampg(b.y & 0xffff0000u), clampg(b.z << 16), clampg(b.z & 0xffff0000u), clampg(b.w << 16), clampg(b.w & 0xffff0000u)};
; #pragma unroll
;                         for (int e = 0; e < 8; ++e) f[e] *= __builtin_amdgcn_rcpf(d[e]); }
;                     f32x4 x0 = acc[ai][bj][m][0], x1 = acc[ai][bj][m][1];
;                     x0[0] *= f[0]; x0[1] *= f[1]; x0[2] *= f[2]; x0[3] *= f[3]; x1[0] *= f[4]; x1[1] *= f[5]; x1[2] *= f[6]; x1[3] *= f[7];
;                     if (br < 2) { acc[ai][bj][m][0] = x0; acc[ai][bj][m][1] = x1; }
;                     else *(u32x4*)(O + (size_t)(ai * HALF + m * 16) * D + HALF * bj) = pack8(x0, x1);
.LBB0_715:
	v_pk_mul_f32 v[38:39], v[38:39], v[142:143]
	v_pk_mul_f32 v[40:41], v[40:41], v[140:141]
	v_pk_mul_f32 v[34:35], v[34:35], v[144:145]
	s_and_b64 vcc, exec, s[6:7]
	v_pk_mul_f32 v[36:37], v[36:37], v[138:139]
	s_cbranch_vccnz .LBB0_717
	v_cvt_pk_bf16_f32 v134, v38, v39
	v_cvt_pk_bf16_f32 v135, v40, v41
	v_cvt_pk_bf16_f32 v137, v36, v37
	v_add_co_u32_e32 v138, vcc, 0x58000, v196
	v_cvt_pk_bf16_f32 v136, v34, v35
	s_nop 0
	v_addc_co_u32_e32 v139, vcc, 0, v197, vcc
	global_store_dwordx4 v[138:139], v[134:137], off
	s_branch .LBB0_718
.LBB0_717:
.LBB0_718:
	s_waitcnt vmcnt(0)
	v_lshlrev_b32_e32 v134, 16, v252
	v_max_u32_e32 v138, 0xda24260, v134
	v_and_b32_e32 v134, 0xffff0000, v252
	v_max_u32_e32 v139, 0xda24260, v134
	v_lshlrev_b32_e32 v134, 16, v253
	v_max_u32_e32 v136, 0xda24260, v134
	v_and_b32_e32 v134, 0xffff0000, v253
	v_max_u32_e32 v137, 0xda24260, v134
	v_lshlrev_b32_e32 v134, 16, v254
	v_max_u32_e32 v140, 0xda24260, v134
	v_and_b32_e32 v134, 0xffff0000, v254
	v_max_u32_e32 v141, 0xda24260, v134
	v_lshlrev_b32_e32 v134, 16, v255
	v_and_b32_e32 v135, 0xffff0000, v255
	v_mov_b32_e32 v252, v130
	v_mov_b32_e32 v253, v131
	v_mov_b32_e32 v254, v132
	v_mov_b32_e32 v255, v133
	v_max_u32_e32 v134, 0xda24260, v134
	v_max_u32_e32 v135, 0xda24260, v135
	s_and_b64 vcc, exec, s[6:7]
	s_mov_b64 s[2:3], -1
	s_cbranch_vccnz .LBB0_720
	s_mov_b64 s[2:3], 0

; __device__ __forceinline__ u32x4 pack8(const f32x4 a, const f32x4 b) { u32x4 w; w.x = cvt_pk_bf16(a[0], a[1]); w.y = cvt_pk_bf16(a[2], a[3]); w.z = cvt_pk_bf16(b[0], b[1]); w.w = cvt_pk_bf16(b[2], b[3]); return w; }
;     __device__ __forceinline__ void operator()(acc_t& acc, const Unit& u, int wr, int wc, int fr, int fq) const {
;     ...
;                     f32x4 x0 = acc[ai][bj][m][0], x1 = acc[ai][bj][m][1];
;                     x0[0] *= f[0]; x0[1] *= f[1]; x0[2] *= f[2]; x0[3] *= f[3]; x1[0] *= f[4]; x1[1] *= f[5]; x1[2] *= f[6]; x1[3] *= f[7];
;                     if (br < 2) { acc[ai][bj][m][0] = x0; acc[ai][bj][m][1] = x1; }
;                     else *(u32x4*)(O + (size_t)(ai * HALF + m * 16) * D + HALF * bj) = pack8(x0, x1);
;                 }
;             asm volatile("" ::: "memory");
;         }
;     }
.LBB0_722:
	v_pk_mul_f32 v[6:7], v[6:7], v[138:139]
	v_pk_mul_f32 v[8:9], v[8:9], v[136:137]
	v_pk_mul_f32 v[2:3], v[2:3], v[140:141]
	s_and_b64 vcc, exec, s[6:7]
	v_pk_mul_f32 v[4:5], v[4:5], v[134:135]
	s_cbranch_vccnz .LBB0_724
	v_cvt_pk_bf16_f32 v130, v6, v7
	v_cvt_pk_bf16_f32 v131, v8, v9
	v_cvt_pk_bf16_f32 v133, v4, v5
	v_add_co_u32_e32 v134, vcc, 0x58000, v196
	v_cvt_pk_bf16_f32 v132, v2, v3
	s_nop 0
	v_addc_co_u32_e32 v135, vcc, 0, v197, vcc
	global_store_dwordx4 v[134:135], v[130:133], off offset:256
	s_branch .LBB0_725
.LBB0_724:
.LBB0_725:
	s_cmp_eq_u32 s44, 2
	s_mov_b64 s[2:3], -1
	s_cbranch_scc1 .LBB0_574
	s_andn2_b64 vcc, exec, s[0:1]
	s_cbranch_vccnz .LBB0_573
	s_barrier
	s_branch .LBB0_573
